# phase 3->4 grid barrier split into arrive and a deferred wait: decode items (independent of phase 3) start before the barrier is released
# speedup vs baseline: 1.0290x; 1.0118x over previous
.LBB0_473:
	s_or_b64 exec, exec, s[8:9]
	v_cvt_f32_u32_e32 v5, v3
	s_waitcnt vmcnt(0)
	v_readfirstlane_b32 s4, v4
	v_sub_u32_e32 v4, 0, v3
	v_rcp_iflag_f32_e32 v5, v5
	v_add_u32_e32 v6, s4, v2
	v_mul_f32_e32 v5, 0x4f7ffffe, v5
	v_cvt_u32_f32_e32 v5, v5
	v_mul_lo_u32 v2, v4, v5
	v_mul_hi_u32 v2, v5, v2
	v_add_u32_e32 v2, v5, v2
	v_mul_hi_u32 v2, v6, v2
	v_mul_lo_u32 v4, v2, v3
	v_sub_u32_e32 v4, v6, v4
	v_add_u32_e32 v5, 1, v2
	v_cmp_ge_u32_e32 vcc, v4, v3
	s_nop 1
	v_cndmask_b32_e32 v2, v2, v5, vcc
	v_sub_u32_e32 v5, v4, v3
	v_cndmask_b32_e32 v4, v4, v5, vcc
	v_add_u32_e32 v5, 1, v2
	v_cmp_ge_u32_e32 vcc, v4, v3
	v_add_u32_e32 v4, 1, v6
	s_nop 0
	v_cndmask_b32_e32 v2, v2, v5, vcc
	v_mul_lo_u32 v5, v3, v2
	v_add_u32_e32 v3, v5, v3
	v_cmp_ne_u32_e32 vcc, v4, v3
	s_and_saveexec_b64 s[4:5], vcc
	s_xor_b64 s[4:5], exec, s[4:5]
	s_cbranch_execz .LBB0_487
	s_waitcnt lgkmcnt(0)
	s_branch .Lp3d_defer
	v_mov_b32_e32 v1, 0x2000
	global_load_dword v1, v1, s[2:3] offset:1024 sc1
	s_add_u32 s44, s2, 0x2400
	s_addc_u32 s45, s3, 0
	s_waitcnt vmcnt(0)
	v_cmp_eq_u32_e32 vcc, v1, v2
	s_and_saveexec_b64 s[8:9], vcc
	s_cbranch_execz .LBB0_486
	s_add_u32 s10, s68, 0x4200
	s_addc_u32 s11, s69, 0
	s_mov_b32 s6, 1
	s_mov_b64 s[46:47], 0
	v_mov_b32_e32 v1, 0
	s_branch .LBB0_477
.Lp3d_defer:
	s_add_u32 s44, s2, 0x2400
	s_addc_u32 s45, s3, 0
	v_mov_b32_e32 v1, 0x24200
	v_mov_b32_e32 v4, 1
	v_mov_b32_e32 v5, s44
	v_mov_b32_e32 v6, s45
	ds_write_b32 v1, v4
	ds_write_b32 v1, v2 offset:4
	ds_write_b32 v1, v5 offset:8
	ds_write_b32 v1, v6 offset:12
	s_branch .LBB0_487

.LBB0_517:
	s_or_b64 exec, exec, s[0:1]
	s_waitcnt lgkmcnt(0)
	s_barrier
	ds_read_b32 v1, v232
	s_mov_b64 s[0:1], -1
	s_waitcnt lgkmcnt(0)
	s_barrier
	v_readfirstlane_b32 s60, v1
	s_cmpk_lt_i32 s60, 0x80
	s_cbranch_scc1 .Lp3d_go
	v_mov_b32_e32 v2, 0x24200
	ds_read_b32 v1, v2
	s_waitcnt lgkmcnt(0)
	v_readfirstlane_b32 s6, v1
	s_cmp_eq_u32 s6, 0
	s_cbranch_scc1 .Lp3d_go
	s_barrier
	s_and_saveexec_b64 s[2:3], s[94:95]
	s_cbranch_execz .Lp3d_wd
	ds_read_b32 v1, v2 offset:8
	s_waitcnt lgkmcnt(0)
	v_readfirstlane_b32 s10, v1
	ds_read_b32 v1, v2 offset:12
	s_waitcnt lgkmcnt(0)
	v_readfirstlane_b32 s11, v1
	ds_read_b32 v1, v2 offset:4
	s_waitcnt lgkmcnt(0)
	ds_write_b32 v2, v3
	s_mov_b32 s6, 0
	s_nop 4
.Lp3d_spin:
	global_load_dword v2, v3, s[10:11] sc1
	s_waitcnt vmcnt(0)
	v_cmp_ne_u32_e32 vcc, v2, v1
	s_cbranch_vccnz .Lp3d_rel
	s_sleep 1
	s_add_i32 s6, s6, 1
	s_cmp_lt_u32 s6, 0x100000
	s_cbranch_scc1 .Lp3d_spin
.Lp3d_rel:
	buffer_inv sc1
	s_waitcnt vmcnt(0)
.Lp3d_wd:
	s_or_b64 exec, exec, s[2:3]
	s_waitcnt lgkmcnt(0)
	s_barrier
.Lp3d_go:
	s_cmpk_gt_i32 s60, 0x58f
	s_cbranch_scc1 .LBB0_512
	s_cmpk_gt_i32 s60, 0x7f
	s_cbranch_scc0 .LBB0_669
	s_cmpk_gt_u32 s60, 0x17f
	s_cbranch_scc0 .LBB0_654
	s_cmpk_gt_u32 s60, 0x19f
	s_cbranch_scc0 .LBB0_614
	s_cmpk_gt_u32 s60, 0x49f
	s_cbranch_scc0 .LBB0_527
	s_lshl_b32 s0, s60, 3
	v_readlane_b32 s1, v245, 59
	s_add_i32 s3, s1, s0
	v_mov_b32_e32 v2, v214
	s_lshl_b32 s0, s3, 1
	s_and_b32 s2, s0, 0x7fffffc0
	s_waitcnt vmcnt(46)
	v_ashrrev_i32_e32 v9, 5, v2
	v_lshlrev_b32_e32 v4, 2, v2
	v_ashrrev_i32_e32 v1, 3, v2
	v_lshlrev_b32_e32 v5, 3, v2
	s_movk_i32 s6, 0x84
	s_cmpk_gt_i32 s3, 0x1ff
	s_mov_b64 s[0:1], -1
	v_and_b32_e32 v2, 0x7c, v4
	v_mul_lo_u32 v8, v9, s6
	v_and_b32_e32 v7, 56, v5
	v_lshlrev_b32_e32 v6, 2, v1
	s_cbranch_scc0 .LBB0_524
	s_lshl_b32 s0, s3, 5
	s_and_b32 s0, s0, 0x3e0
	v_readlane_b32 s16, v245, 18
	s_add_i32 s44, s2, 0xfffffc00
	s_lshl_b32 s1, s0, 2
	v_readlane_b32 s24, v245, 26
	v_add_u32_e32 v4, s44, v9
	v_readlane_b32 s25, v245, 27
	s_add_u32 s6, s24, s1
	s_addc_u32 s7, s25, 0
	v_ashrrev_i32_e32 v5, 31, v4
	v_lshl_add_u64 v[10:11], s[6:7], 0, v[2:3]
	v_lshlrev_b64 v[4:5], 12, v[4:5]
	v_lshl_add_u64 v[4:5], v[10:11], 0, v[4:5]
	v_add_co_u32_e32 v10, vcc, s8, v4
	global_load_dword v12, v[4:5], off nt
	s_nop 0
	v_addc_co_u32_e32 v11, vcc, 0, v5, vcc
	global_load_dword v13, v[10:11], off nt
	v_add_co_u32_e32 v10, vcc, s61, v4
	s_movk_i32 s1, 0x6000
	s_nop 0
	v_addc_co_u32_e32 v11, vcc, 0, v5, vcc
	global_load_dword v14, v[10:11], off nt
	v_add_co_u32_e32 v10, vcc, s1, v4
	s_mov_b32 s1, 0x8000
	s_nop 0
	v_addc_co_u32_e32 v11, vcc, 0, v5, vcc
	global_load_dword v15, v[10:11], off nt
	v_add_co_u32_e32 v10, vcc, s1, v4
	s_mov_b32 s1, 0xa000
	s_nop 0
	v_addc_co_u32_e32 v11, vcc, 0, v5, vcc
	global_load_dword v16, v[10:11], off nt
	v_add_co_u32_e32 v10, vcc, s1, v4
	s_mov_b32 s1, 0xc000
	s_nop 0
	v_addc_co_u32_e32 v11, vcc, 0, v5, vcc
	global_load_dword v17, v[10:11], off nt
	v_add_co_u32_e32 v10, vcc, s1, v4
	s_mov_b32 s1, 0xe000
	s_nop 0
	v_addc_co_u32_e32 v11, vcc, 0, v5, vcc
	global_load_dword v18, v[10:11], off nt
	v_add_co_u32_e32 v10, vcc, s1, v4
	s_mov_b32 s1, 0x12000
	s_nop 0
	v_addc_co_u32_e32 v11, vcc, 0, v5, vcc
	global_load_dword v19, v[10:11], off nt
	v_add_co_u32_e32 v10, vcc, s9, v4
	s_lshl_b64 s[6:7], s[44:45], 1
	s_nop 0
	v_addc_co_u32_e32 v11, vcc, 0, v5, vcc
	global_load_dword v20, v[10:11], off nt
	v_add_co_u32_e32 v10, vcc, s1, v4
	s_mov_b32 s1, 0x14000
	s_nop 0
	v_addc_co_u32_e32 v11, vcc, 0, v5, vcc
	global_load_dword v21, v[10:11], off nt
	v_add_co_u32_e32 v10, vcc, s1, v4
	s_mov_b32 s1, 0x16000
	s_nop 0
	v_addc_co_u32_e32 v11, vcc, 0, v5, vcc
	global_load_dword v22, v[10:11], off nt
	v_add_co_u32_e32 v10, vcc, s1, v4
	s_mov_b32 s1, 0x18000
	s_nop 0
	v_addc_co_u32_e32 v11, vcc, 0, v5, vcc
	global_load_dword v23, v[10:11], off nt
	v_add_co_u32_e32 v10, vcc, s1, v4
	s_mov_b32 s1, 0x1a000
	s_nop 0
	v_addc_co_u32_e32 v11, vcc, 0, v5, vcc
	global_load_dword v24, v[10:11], off nt
	v_add_co_u32_e32 v10, vcc, s1, v4
	s_mov_b32 s1, 0x1c000
	s_nop 0
	v_addc_co_u32_e32 v11, vcc, 0, v5, vcc
	global_load_dword v25, v[10:11], off nt
	v_add_co_u32_e32 v10, vcc, s1, v4
	s_mov_b32 s1, 0x1e000
	s_nop 0
	v_addc_co_u32_e32 v11, vcc, 0, v5, vcc
	global_load_dword v26, v[10:11], off nt
	v_add_co_u32_e32 v10, vcc, s1, v4
	s_mov_b32 s1, 0x22000
	s_nop 0
	v_addc_co_u32_e32 v11, vcc, 0, v5, vcc
	global_load_dword v27, v[10:11], off nt
	v_add_co_u32_e32 v10, vcc, s77, v4
	s_add_u32 s6, s97, s6
	s_nop 0
	v_addc_co_u32_e32 v11, vcc, 0, v5, vcc
	global_load_dword v28, v[10:11], off nt
	v_add_co_u32_e32 v10, vcc, s1, v4
	s_mov_b32 s1, 0x24000
	s_nop 0
	v_addc_co_u32_e32 v11, vcc, 0, v5, vcc
	global_load_dword v29, v[10:11], off nt
	v_add_co_u32_e32 v10, vcc, s1, v4
	s_mov_b32 s1, 0x26000
	s_nop 0
	v_addc_co_u32_e32 v11, vcc, 0, v5, vcc
	global_load_dword v30, v[10:11], off nt
	v_add_co_u32_e32 v10, vcc, s1, v4
	s_mov_b32 s1, 0x28000
	s_nop 0
	v_addc_co_u32_e32 v11, vcc, 0, v5, vcc
	global_load_dword v31, v[10:11], off nt
	v_add_co_u32_e32 v10, vcc, s1, v4
	s_mov_b32 s1, 0x2a000
	s_nop 0
	v_addc_co_u32_e32 v11, vcc, 0, v5, vcc
	global_load_dword v32, v[10:11], off nt
	v_add_co_u32_e32 v10, vcc, s1, v4
	s_mov_b32 s1, 0x2c000
	s_nop 0
	v_addc_co_u32_e32 v11, vcc, 0, v5, vcc
	global_load_dword v33, v[10:11], off nt
	v_add_co_u32_e32 v10, vcc, s1, v4
	s_mov_b32 s1, 0x2e000
	s_nop 0
	v_addc_co_u32_e32 v11, vcc, 0, v5, vcc
	global_load_dword v34, v[10:11], off nt
	v_add_co_u32_e32 v10, vcc, s1, v4
	s_mov_b32 s1, 0x32000
	s_nop 0
	v_addc_co_u32_e32 v11, vcc, 0, v5, vcc
	global_load_dword v35, v[10:11], off nt
	v_add_co_u32_e32 v10, vcc, s40, v4
	v_readlane_b32 s10, v245, 53
	s_nop 0
	v_addc_co_u32_e32 v11, vcc, 0, v5, vcc
	global_load_dword v36, v[10:11], off nt
	v_add_co_u32_e32 v10, vcc, s1, v4
	s_mov_b32 s1, 0x34000
	s_nop 0
	v_addc_co_u32_e32 v11, vcc, 0, v5, vcc
	global_load_dword v37, v[10:11], off nt
	v_add_co_u32_e32 v10, vcc, s1, v4
	s_mov_b32 s1, 0x36000
	s_nop 0
	v_addc_co_u32_e32 v11, vcc, 0, v5, vcc
	global_load_dword v38, v[10:11], off nt
	v_add_co_u32_e32 v10, vcc, s1, v4
	s_mov_b32 s1, 0x38000
	s_nop 0
	v_addc_co_u32_e32 v11, vcc, 0, v5, vcc
	global_load_dword v39, v[10:11], off nt
	v_add_co_u32_e32 v10, vcc, s1, v4
	s_mov_b32 s1, 0x3a000
	s_nop 0
	v_addc_co_u32_e32 v11, vcc, 0, v5, vcc
	global_load_dword v40, v[10:11], off nt
	v_add_co_u32_e32 v10, vcc, s1, v4
	s_mov_b32 s1, 0x3c000
	s_nop 0
	v_addc_co_u32_e32 v11, vcc, 0, v5, vcc
	global_load_dword v41, v[10:11], off nt
	v_add_co_u32_e32 v10, vcc, s1, v4
	s_mov_b32 s1, 0x3e000
	s_nop 0
	v_addc_co_u32_e32 v11, vcc, 0, v5, vcc
	v_add_co_u32_e32 v4, vcc, s1, v4
	global_load_dword v10, v[10:11], off nt
	s_nop 0
	v_addc_co_u32_e32 v5, vcc, 0, v5, vcc
	global_load_dword v4, v[4:5], off nt
	v_readlane_b32 s1, v245, 60
	s_addc_u32 s7, s10, s7
	v_readlane_b32 s17, v245, 19
	v_add3_u32 v5, s1, v2, v8
	v_add_u32_e32 v11, 0x1000, v5
	s_waitcnt vmcnt(30)
	ds_write2_b32 v11, v12, v13 offset1:66
	s_waitcnt vmcnt(28)
	ds_write2_b32 v11, v14, v15 offset0:132 offset1:198
	v_add_u32_e32 v11, 0x1400, v5
	s_waitcnt vmcnt(26)
	ds_write2_b32 v11, v16, v17 offset0:8 offset1:74
	s_waitcnt vmcnt(24)
	ds_write2_b32 v11, v18, v19 offset0:140 offset1:206
	v_add_u32_e32 v11, 0x1800, v5
	s_waitcnt vmcnt(22)
	ds_write2_b32 v11, v20, v21 offset0:16 offset1:82
	s_waitcnt vmcnt(20)
	ds_write2_b32 v11, v22, v23 offset0:148 offset1:214
	v_add_u32_e32 v11, 0x1c00, v5
	s_waitcnt vmcnt(18)
	ds_write2_b32 v11, v24, v25 offset0:24 offset1:90
	s_waitcnt vmcnt(16)
	ds_write2_b32 v11, v26, v27 offset0:156 offset1:222
	v_add_u32_e32 v11, 0x2000, v5
	s_waitcnt vmcnt(14)
	ds_write2_b32 v11, v28, v29 offset0:32 offset1:98
	s_waitcnt vmcnt(12)
	ds_write2_b32 v11, v30, v31 offset0:164 offset1:230
	v_add_u32_e32 v11, 0x2400, v5
	s_waitcnt vmcnt(10)
	ds_write2_b32 v11, v32, v33 offset0:40 offset1:106
	s_waitcnt vmcnt(8)
	ds_write2_b32 v11, v34, v35 offset0:172 offset1:238
	v_add_u32_e32 v11, 0x2800, v5
	v_add_u32_e32 v5, 0x2c00, v5
	s_waitcnt vmcnt(6)
	ds_write2_b32 v11, v36, v37 offset0:48 offset1:114
	s_waitcnt vmcnt(4)
	ds_write2_b32 v11, v38, v39 offset0:180 offset1:246
	s_waitcnt vmcnt(2)
	ds_write2_b32 v5, v40, v41 offset0:56 offset1:122
	s_waitcnt vmcnt(0)
	ds_write2_b32 v5, v10, v4 offset0:188 offset1:254
	v_mul_u32_u24_e32 v10, 0x84, v7
	s_waitcnt lgkmcnt(0)
	v_add3_u32 v10, s1, v10, v6
	v_add_u32_e32 v32, 0x1000, v10
	ds_read2_b32 v[14:15], v32 offset0:33 offset1:41
	ds_read2_b32 v[16:17], v32 offset1:8
	ds_read2_b32 v[18:19], v32 offset0:66 offset1:74
	ds_read2_b32 v[20:21], v32 offset0:99 offset1:107
	v_lshlrev_b32_e32 v4, 1, v7
	v_mov_b32_e32 v5, v3
	s_waitcnt lgkmcnt(3)
	v_bfe_u32 v11, v14, 16, 1
	s_waitcnt lgkmcnt(2)
	v_bfe_u32 v10, v16, 16, 1
	v_add3_u32 v10, v16, v10, s88
	v_lshl_add_u64 v[4:5], s[6:7], 0, v[4:5]
	v_lshrrev_b32_e32 v10, 16, v10
	v_add3_u32 v11, v14, v11, s88
	s_mov_b32 s6, 0xffff0000
	ds_read2_b32 v[22:23], v32 offset0:132 offset1:140
	ds_read2_b32 v[24:25], v32 offset0:165 offset1:173
	v_and_or_b32 v10, v11, s6, v10
	s_waitcnt lgkmcnt(3)
	v_bfe_u32 v11, v18, 16, 1
	v_add3_u32 v11, v18, v11, s88
	s_waitcnt lgkmcnt(2)
	v_bfe_u32 v12, v20, 16, 1
	v_lshrrev_b32_e32 v11, 16, v11
	v_add3_u32 v12, v20, v12, s88
	ds_read2_b32 v[26:27], v32 offset0:198 offset1:206
	ds_read2_b32 v[28:29], v32 offset0:231 offset1:239
	v_and_or_b32 v11, v12, s6, v11
	s_waitcnt lgkmcnt(3)
	v_bfe_u32 v12, v22, 16, 1
	v_add3_u32 v12, v22, v12, s88
	s_waitcnt lgkmcnt(2)
	v_bfe_u32 v13, v24, 16, 1
	v_lshrrev_b32_e32 v12, 16, v12
	v_add3_u32 v13, v24, v13, s88
	v_and_or_b32 v12, v13, s6, v12
	s_waitcnt lgkmcnt(1)
	v_bfe_u32 v13, v26, 16, 1
	v_add3_u32 v13, v26, v13, s88
	s_waitcnt lgkmcnt(0)
	v_bfe_u32 v14, v28, 16, 1
	v_lshrrev_b32_e32 v13, 16, v13
	v_add3_u32 v14, v28, v14, s88
	v_add_u32_e32 v33, s0, v1
	s_movk_i32 s7, 0x1600
	v_and_or_b32 v13, v14, s6, v13
	v_mad_i64_i32 v[30:31], s[0:1], v33, s7, v[4:5]
	global_store_dwordx4 v[30:31], v[10:13], off
	v_bfe_u32 v14, v29, 16, 1
	v_add3_u32 v14, v29, v14, s88
	v_bfe_u32 v10, v17, 16, 1
	v_add3_u32 v10, v17, v10, s88
	v_bfe_u32 v11, v15, 16, 1
	v_lshrrev_b32_e32 v10, 16, v10
	v_add3_u32 v11, v15, v11, s88
	v_and_or_b32 v10, v11, s6, v10
	v_bfe_u32 v11, v19, 16, 1
	v_add3_u32 v11, v19, v11, s88
	v_bfe_u32 v12, v21, 16, 1
	v_lshrrev_b32_e32 v11, 16, v11
	v_add3_u32 v12, v21, v12, s88
	v_and_or_b32 v11, v12, s6, v11
	v_bfe_u32 v12, v23, 16, 1
	v_add3_u32 v12, v23, v12, s88
	v_bfe_u32 v13, v25, 16, 1
	v_lshrrev_b32_e32 v12, 16, v12
	v_add3_u32 v13, v25, v13, s88
	v_and_or_b32 v12, v13, s6, v12
	v_bfe_u32 v13, v27, 16, 1
	v_add3_u32 v13, v27, v13, s88
	v_lshrrev_b32_e32 v13, 16, v13
	v_and_or_b32 v13, v14, s6, v13
	v_add_u32_e32 v14, 8, v33
	v_mad_i64_i32 v[14:15], s[0:1], v14, s7, v[4:5]
	global_store_dwordx4 v[14:15], v[10:13], off
	ds_read2_b32 v[14:15], v32 offset0:49 offset1:57
	ds_read2_b32 v[16:17], v32 offset0:16 offset1:24
	ds_read2_b32 v[18:19], v32 offset0:82 offset1:90
	ds_read2_b32 v[20:21], v32 offset0:115 offset1:123
	ds_read2_b32 v[22:23], v32 offset0:148 offset1:156
	ds_read2_b32 v[24:25], v32 offset0:181 offset1:189
	ds_read2_b32 v[26:27], v32 offset0:214 offset1:222
	ds_read2_b32 v[28:29], v32 offset0:247 offset1:255
	s_waitcnt lgkmcnt(7)
	v_bfe_u32 v11, v14, 16, 1
	s_waitcnt lgkmcnt(6)
	v_bfe_u32 v10, v16, 16, 1
	v_add3_u32 v10, v16, v10, s88
	v_lshrrev_b32_e32 v10, 16, v10
	v_add3_u32 v11, v14, v11, s88
	v_and_or_b32 v10, v11, s6, v10
	s_waitcnt lgkmcnt(5)
	v_bfe_u32 v11, v18, 16, 1
	v_add3_u32 v11, v18, v11, s88
	s_waitcnt lgkmcnt(4)
	v_bfe_u32 v12, v20, 16, 1
	v_lshrrev_b32_e32 v11, 16, v11
	v_add3_u32 v12, v20, v12, s88
	v_and_or_b32 v11, v12, s6, v11
	s_waitcnt lgkmcnt(3)
	v_bfe_u32 v12, v22, 16, 1
	v_add3_u32 v12, v22, v12, s88
	s_waitcnt lgkmcnt(2)
	v_bfe_u32 v13, v24, 16, 1
	v_lshrrev_b32_e32 v12, 16, v12
	v_add3_u32 v13, v24, v13, s88
	v_and_or_b32 v12, v13, s6, v12
	s_waitcnt lgkmcnt(1)
	v_bfe_u32 v13, v26, 16, 1
	v_add3_u32 v13, v26, v13, s88
	s_waitcnt lgkmcnt(0)
	v_bfe_u32 v14, v28, 16, 1
	v_lshrrev_b32_e32 v13, 16, v13
	v_add3_u32 v14, v28, v14, s88
	v_and_or_b32 v13, v14, s6, v13
	v_add_u32_e32 v14, 16, v33
	v_mad_i64_i32 v[30:31], s[0:1], v14, s7, v[4:5]
	global_store_dwordx4 v[30:31], v[10:13], off
	v_bfe_u32 v14, v29, 16, 1
	v_add3_u32 v14, v29, v14, s88
	v_bfe_u32 v10, v17, 16, 1
	v_add3_u32 v10, v17, v10, s88
	v_bfe_u32 v11, v15, 16, 1
	v_lshrrev_b32_e32 v10, 16, v10
	v_add3_u32 v11, v15, v11, s88
	v_and_or_b32 v10, v11, s6, v10
	v_bfe_u32 v11, v19, 16, 1
	v_add3_u32 v11, v19, v11, s88
	v_bfe_u32 v12, v21, 16, 1
	v_lshrrev_b32_e32 v11, 16, v11
	v_add3_u32 v12, v21, v12, s88
	v_and_or_b32 v11, v12, s6, v11
	v_bfe_u32 v12, v23, 16, 1
	v_add3_u32 v12, v23, v12, s88
	v_bfe_u32 v13, v25, 16, 1
	v_lshrrev_b32_e32 v12, 16, v12
	v_add3_u32 v13, v25, v13, s88
	v_and_or_b32 v12, v13, s6, v12
	v_bfe_u32 v13, v27, 16, 1
	v_add3_u32 v13, v27, v13, s88
	v_lshrrev_b32_e32 v13, 16, v13
	v_and_or_b32 v13, v14, s6, v13
	v_add_u32_e32 v14, 24, v33
	v_mad_i64_i32 v[4:5], s[0:1], v14, s7, v[4:5]
	global_store_dwordx4 v[4:5], v[10:13], off
	s_waitcnt lgkmcnt(0)
	v_readlane_b32 s18, v245, 20
	v_readlane_b32 s19, v245, 21
	v_readlane_b32 s20, v245, 22
	v_readlane_b32 s21, v245, 23
	v_readlane_b32 s22, v245, 24
	v_readlane_b32 s23, v245, 25
	v_readlane_b32 s26, v245, 28
	v_readlane_b32 s27, v245, 29
	v_readlane_b32 s28, v245, 30
	v_readlane_b32 s29, v245, 31
	v_readlane_b32 s30, v245, 32
	v_readlane_b32 s31, v245, 33
	s_mov_b64 s[0:1], 0
